# NSA: row-max across 16-lane rows via v_permlane16_swap/v_permlane32_swap instead of two ds_bpermute round trips per tile
# speedup vs baseline: 1.0144x; 1.0025x over previous
; #define EXP2F(x) __builtin_amdgcn_exp2f(x)
; #define SB0 __builtin_amdgcn_sched_barrier(0)
; __device__ __forceinline__ void qk64_lim(const bf16x8 (&kq)[8], const bf16x8 (&qf)[2], float scale, int lim2,
;                                          f32x4 (&st)[4]) {
; #pragma unroll
;   for (int kt = 0; kt < 4; ++kt) {
;     f32x4 z = {0.f, 0.f, 0.f, 0.f};
;     z = mfma16(kq[2 * kt], qf[0], z);
;     z = mfma16(kq[2 * kt + 1], qf[1], z);
; #pragma unroll
;     for (int r = 0; r < 4; ++r) st[kt][r] = ((kt * 16 + r) <= lim2) ? z[r] * scale : -INFINITY;
;   }
; }
; __device__ __forceinline__ void phase_nsa_attn(const Params& p, char* smem, volatile LAS unsigned* vb_) {
;     ...
;         for (int i = 0; i < ntile; ++i) {
;           const int n0 = i * 64;
;           const int nn = (i + 1 < ntile ? i + 1 : i) * 64;
;           f32x4 st[4];
;           qk64_lim(kA, qf, scale, nvalid - 1 - n0 - q * 4, st);
;           SB0;
;           k_load64(kA, Kb + (size_t)nn * 64, lane);
;           SB0;
;           float mx = -1e30f;
; #pragma unroll
;           for (int kt = 0; kt < 4; ++kt)
; #pragma unroll
;             for (int r = 0; r < 4; ++r) mx = fmaxf(mx, st[kt][r]);
;           mx = fmaxf(mx, __shfl_xor(mx, 16));
;           mx = fmaxf(mx, __shfl_xor(mx, 32));
;           const float mnew = fmaxf(m, mx);
;           float ps = 0.f;
; #pragma unroll
;           for (int kt = 0; kt < 4; ++kt)
; #pragma unroll
;             for (int r = 0; r < 4; ++r) ps += EXP2F(st[kt][r] - mnew);
;           lsum = lsum * EXP2F(m - mnew) + ps;
;           m = mnew;
;         }
.LBB0_94:
	s_waitcnt vmcnt(7)
	v_mfma_f32_16x16x32_bf16 v[40:43], v[40:43], v[4:7], 0
	s_add_i32 s11, s20, 1
	v_mov_b32_e32 v44, v0
	v_mov_b32_e32 v0, s20
	s_waitcnt vmcnt(6)
	v_mfma_f32_16x16x32_bf16 v[36:39], v[36:39], v[8:11], v[40:43]
	v_mov_b32_e32 v45, s11
	v_cmp_lt_i32_e32 vcc, s11, v159
	v_mov_b32_e32 v3, v180
	s_waitcnt vmcnt(5)
	v_mfma_f32_16x16x32_bf16 v[32:35], v[32:35], v[4:7], 0
	v_cndmask_b32_e32 v0, v0, v45, vcc
	s_nop 1
	v_mul_f32_e32 v36, 0x3e38aa3b, v36
	v_cmp_lt_i32_e32 vcc, -1, v2
	s_waitcnt vmcnt(4)
	v_mfma_f32_16x16x32_bf16 v[28:31], v[28:31], v[8:11], v[32:35]
	v_lshlrev_b32_e32 v0, 6, v0
	v_cndmask_b32_e32 v45, v203, v36, vcc
	v_mul_f32_e32 v36, 0x3e38aa3b, v37
	s_waitcnt vmcnt(3)
	v_mfma_f32_16x16x32_bf16 v[24:27], v[24:27], v[4:7], 0
	v_cmp_lt_i32_e32 vcc, 0, v2
	s_nop 1
	v_mul_f32_e32 v28, 0x3e38aa3b, v28
	v_cndmask_b32_e32 v46, v203, v36, vcc
	v_mul_f32_e32 v36, 0x3e38aa3b, v38
	v_cmp_lt_i32_e32 vcc, 1, v2
	s_waitcnt vmcnt(2)
	v_mfma_f32_16x16x32_bf16 v[20:23], v[20:23], v[8:11], v[24:27]
	v_cndmask_b32_e32 v47, v203, v36, vcc
	v_mul_f32_e32 v36, 0x3e38aa3b, v39
	v_cmp_lt_i32_e32 vcc, 2, v2
	s_waitcnt vmcnt(1)
	v_mfma_f32_16x16x32_bf16 v[16:19], v[16:19], v[4:7], 0
	s_nop 2
	v_mul_f32_e32 v20, 0x3e38aa3b, v20
	v_cndmask_b32_e32 v48, v203, v36, vcc
	v_cmp_lt_i32_e32 vcc, 15, v2
	s_waitcnt vmcnt(0)
	v_mfma_f32_16x16x32_bf16 v[12:15], v[12:15], v[8:11], v[16:19]
	v_cndmask_b32_e32 v49, v203, v28, vcc
	v_mul_f32_e32 v28, 0x3e38aa3b, v29
	v_cmp_lt_i32_e32 vcc, 16, v2
	s_nop 1
	v_cndmask_b32_e32 v50, v203, v28, vcc
	v_mul_f32_e32 v28, 0x3e38aa3b, v30
	v_cmp_lt_i32_e32 vcc, 17, v2
	v_mul_f32_e32 v12, 0x3e38aa3b, v12
	s_nop 0
	v_cndmask_b32_e32 v51, v203, v28, vcc
	v_mul_f32_e32 v28, 0x3e38aa3b, v31
	v_cmp_lt_i32_e32 vcc, 18, v2
	s_nop 1
	v_cndmask_b32_e32 v52, v203, v28, vcc
	v_cmp_lt_i32_e32 vcc, 31, v2
	s_nop 1
	v_cndmask_b32_e32 v53, v203, v20, vcc
	v_mul_f32_e32 v20, 0x3e38aa3b, v21
	v_cmp_lt_i32_e32 vcc, 32, v2
	s_nop 1
	v_cndmask_b32_e32 v54, v203, v20, vcc
	v_mul_f32_e32 v20, 0x3e38aa3b, v22
	v_cmp_lt_i32_e32 vcc, 33, v2
	s_nop 1
	v_cndmask_b32_e32 v55, v203, v20, vcc
	v_mul_f32_e32 v20, 0x3e38aa3b, v23
	v_cmp_lt_i32_e32 vcc, 34, v2
	s_nop 1
	v_cndmask_b32_e32 v56, v203, v20, vcc
	v_cmp_lt_i32_e32 vcc, 47, v2
	s_nop 1
	v_cndmask_b32_e32 v57, v203, v12, vcc
	v_mul_f32_e32 v12, 0x3e38aa3b, v13
	v_cmp_lt_i32_e32 vcc, 48, v2
	s_nop 1
	v_cndmask_b32_e32 v58, v203, v12, vcc
	v_mul_f32_e32 v12, 0x3e38aa3b, v14
	v_cmp_lt_i32_e32 vcc, 49, v2
	s_nop 1
	v_cndmask_b32_e32 v59, v203, v12, vcc
	v_mul_f32_e32 v12, 0x3e38aa3b, v15
	v_cmp_lt_i32_e32 vcc, 50, v2
	s_nop 1
	v_cndmask_b32_e32 v60, v203, v12, vcc
	v_lshlrev_b64 v[12:13], 7, v[0:1]
	v_lshl_add_u64 v[12:13], v[122:123], 0, v[12:13]
	global_load_dwordx4 v[40:43], v[12:13], off
	global_load_dwordx4 v[36:39], v[12:13], off offset:1024
	global_load_dwordx4 v[32:35], v[12:13], off offset:2048
	global_load_dwordx4 v[28:31], v[12:13], off offset:3072
	v_add_co_u32_e32 v12, vcc, s33, v12
	s_nop 1
	v_addc_co_u32_e32 v13, vcc, 0, v13, vcc
	global_load_dwordx4 v[24:27], v[12:13], off
	global_load_dwordx4 v[20:23], v[12:13], off offset:1024
	global_load_dwordx4 v[16:19], v[12:13], off offset:2048
	s_nop 0
	global_load_dwordx4 v[12:15], v[12:13], off offset:3072
	v_max3_f32 v0, v45, s3, v46
	v_max3_f32 v0, v0, v47, v48
	v_max3_f32 v0, v0, v49, v50
	v_max3_f32 v0, v0, v51, v52
	v_max3_f32 v0, v0, v53, v54
	v_max3_f32 v0, v0, v55, v56
	v_max3_f32 v0, v0, v57, v58
	v_max3_f32 v0, v0, v59, v60
	v_mov_b32_e32 v61, v0
	v_cmp_eq_u32_e32 vcc, s11, v159
	v_subrev_u32_e32 v2, 64, v2
	s_or_b64 s[12:13], vcc, s[12:13]
	s_mov_b32 s20, s11
	v_permlane16_swap_b32_e32 v61, v0
	v_max_f32_e32 v0, v0, v61
	v_mov_b32_e32 v61, v0
	s_nop 1
	v_permlane32_swap_b32_e32 v61, v0
	v_max3_f32 v180, v3, v0, v61
	v_sub_f32_e32 v0, v45, v180
	v_sub_f32_e32 v45, v46, v180
	v_exp_f32_e32 v0, v0
	v_sub_f32_e32 v46, v47, v180
	v_exp_f32_e32 v45, v45
	v_sub_f32_e32 v47, v48, v180
	v_exp_f32_e32 v46, v46
	v_sub_f32_e32 v48, v49, v180
	v_exp_f32_e32 v47, v47
	v_sub_f32_e32 v49, v50, v180
	v_exp_f32_e32 v48, v48
	v_add_f32_e32 v0, 0, v0
	v_sub_f32_e32 v50, v51, v180
	v_exp_f32_e32 v49, v49
	v_add_f32_e32 v0, v45, v0
	v_add_f32_e32 v0, v46, v0
	v_exp_f32_e32 v45, v50
	v_sub_f32_e32 v46, v52, v180
	v_add_f32_e32 v0, v47, v0
	v_exp_f32_e32 v46, v46
	v_sub_f32_e32 v47, v53, v180
	v_add_f32_e32 v0, v48, v0
	v_exp_f32_e32 v47, v47
	v_add_f32_e32 v0, v49, v0
	v_add_f32_e32 v0, v45, v0
	v_sub_f32_e32 v45, v54, v180
	v_add_f32_e32 v0, v46, v0
	v_exp_f32_e32 v45, v45
	v_sub_f32_e32 v46, v55, v180
	v_add_f32_e32 v0, v47, v0
	v_exp_f32_e32 v46, v46
	v_sub_f32_e32 v47, v56, v180
	v_exp_f32_e32 v47, v47
	v_sub_f32_e32 v48, v57, v180
	v_exp_f32_e32 v48, v48
	v_add_f32_e32 v0, v45, v0
	v_sub_f32_e32 v45, v58, v180
	v_add_f32_e32 v0, v46, v0
	v_exp_f32_e32 v45, v45
	v_sub_f32_e32 v46, v59, v180
	v_add_f32_e32 v0, v47, v0
	v_exp_f32_e32 v46, v46
	v_sub_f32_e32 v47, v60, v180
	v_exp_f32_e32 v47, v47
	v_sub_f32_e32 v3, v3, v180
	v_add_f32_e32 v0, v48, v0
	v_exp_f32_e32 v3, v3
	v_add_f32_e32 v0, v45, v0
	v_add_f32_e32 v0, v46, v0
	v_add_f32_e32 v0, v47, v0
	v_fmac_f32_e32 v0, v44, v3
	s_andn2_b64 exec, exec, s[12:13]
	s_cbranch_execnz .LBB0_94
; #define SB0 __builtin_amdgcn_sched_barrier(0)
; __device__ __forceinline__ void phase_nsa_attn(const Params& p, char* smem, volatile LAS unsigned* vb_) {
;     ...
;         lsum += __shfl_xor(lsum, 16);
;         lsum += __shfl_xor(lsum, 32);
;         const float invl = (lsum > 0.f) ? 1.0f / lsum : 0.f;
;         f32x4 o[4];
; #pragma unroll
;         for (int dt = 0; dt < 4; ++dt) o[dt] = (f32x4){0.f, 0.f, 0.f, 0.f};
;         float carry = 0.f;
;       SB0;
;         k_load64(kA, Kb, lane);
;       SB0;
;         v_load64(vA, Vb, lane);
;       SB0;
	s_or_b64 exec, exec, s[12:13]
	ds_bpermute_b32 v2, v167, v0
	v_mov_b32_e32 v181, 0
	s_waitcnt lgkmcnt(0)
	v_add_f32_e32 v0, v0, v2
	ds_bpermute_b32 v2, v168, v0
	s_waitcnt lgkmcnt(0)
	v_add_f32_e32 v0, v0, v2
	v_div_scale_f32 v2, s[12:13], v0, v0, 1.0
	v_rcp_f32_e32 v3, v2
	s_waitcnt vmcnt(0)
	v_fma_f32 v12, -v2, v3, 1.0
	v_fmac_f32_e32 v3, v12, v3
	v_div_scale_f32 v12, vcc, 1.0, v0, 1.0
	v_mul_f32_e32 v13, v12, v3
	v_fma_f32 v14, -v2, v13, v12
	v_fmac_f32_e32 v13, v14, v3
	v_fma_f32 v2, -v2, v13, v12
	v_div_fmas_f32 v2, v2, v3, v13
	v_div_fixup_f32 v2, v2, v0, 1.0
	v_cmp_lt_f32_e32 vcc, 0, v0
	s_nop 1
	v_cndmask_b32_e32 v2, 0, v2, vcc
	global_load_dwordx4 v[68:71], v[122:123], off
	global_load_dwordx4 v[64:67], v[122:123], off offset:1024
	global_load_dwordx4 v[60:63], v[122:123], off offset:2048
	global_load_dwordx4 v[52:55], v[122:123], off offset:3072
	global_load_dwordx4 v[44:47], v[124:125], off
	global_load_dwordx4 v[40:43], v[126:127], off
	global_load_dwordx4 v[36:39], v[128:129], off
	global_load_dwordx4 v[32:35], v[130:131], off
	global_load_dwordx4 v[24:27], v[132:133], off
	global_load_dwordx4 v[12:15], v[132:133], off offset:1024
	global_load_dwordx4 v[80:83], v[132:133], off offset:2048
	global_load_dwordx4 v[84:87], v[132:133], off offset:3072
	global_load_dwordx4 v[28:31], v[134:135], off
	global_load_dwordx4 v[20:23], v[136:137], off
	global_load_dwordx4 v[88:91], v[138:139], off
	global_load_dwordx4 v[16:19], v[140:141], off
	v_mov_b32_e32 v3, v2
	s_mov_b32 s11, 0
	s_mov_b64 s[12:13], 0
	v_mov_b32_e32 v182, v176
	v_mov_b32_e32 v76, 0
	v_mov_b32_e32 v77, v181
	v_mov_b32_e32 v78, v181
	v_mov_b32_e32 v79, v181
	v_mov_b32_e32 v48, 0
	v_mov_b32_e32 v49, v181
	v_mov_b32_e32 v50, v181
	v_mov_b32_e32 v51, v181
	v_mov_b32_e32 v56, 0
	v_mov_b32_e32 v57, v181
	v_mov_b32_e32 v58, v181
	v_mov_b32_e32 v59, v181
	v_mov_b32_e32 v72, 0
	v_mov_b32_e32 v73, v181
	v_mov_b32_e32 v74, v181
	v_mov_b32_e32 v75, v181
	s_branch .LBB0_97

; #define EXP2F(x) __builtin_amdgcn_exp2f(x)
; #define SB0 __builtin_amdgcn_sched_barrier(0)
; __device__ __forceinline__ void softmax_update(f32x4 (&st)[4], float& m, float& lsum, f32x4 (&o)[4]) {
;   float mx = -1e30f;
; #pragma unroll
;   for (int kt = 0; kt < 4; ++kt)
; #pragma unroll
;     for (int r = 0; r < 4; ++r) mx = fmaxf(mx, st[kt][r]);
;   mx = fmaxf(mx, __shfl_xor(mx, 16));
;   mx = fmaxf(mx, __shfl_xor(mx, 32));
;   const float mnew = fmaxf(m, mx);
;   const float alpha = EXP2F(m - mnew);
;   float ps = 0.f;
; #pragma unroll
;   for (int kt = 0; kt < 4; ++kt)
; #pragma unroll
;     for (int r = 0; r < 4; ++r) {
;       const float pv = EXP2F(st[kt][r] - mnew);
;       st[kt][r] = pv;
;       ps += pv;
;     }
;   lsum = lsum * alpha + ps;
;   m = mnew;
;   if (__builtin_amdgcn_ballot_w64(alpha != 1.0f)) {
; #pragma unroll
;     for (int dt = 0; dt < 4; ++dt) o[dt] *= alpha;
;   }
; __device__ __forceinline__ void phase_nsa_attn(const Params& p, char* smem, volatile LAS unsigned* vb_) {
;     ...
;       for (int i = 0; i < ntile; ++i) {
;         const int k0 = lo + i * 64;
;         const int kx = lo + (i + 1 < ntile ? i + 1 : i) * 64;
;         f32x4 st[4];
;         qk64(kA, qf, scale, [&](int ko) { const int ks = k0 + ko; return (ks <= s) && (ks + 512 > s); }, lane, st);
;         SB0;
;         k_load64(kA, Kw + (size_t)kx * 64, lane);
;         SB0;
;         softmax_update(st, m, lsum, o);
;         pv64(vA, st, o);
;         SB0;
;         v_load64(vA, Vw + (size_t)kx * 64, lane);
;         SB0;
;       }
.LBB0_103:
	s_waitcnt vmcnt(15)
	v_mfma_f32_16x16x32_bf16 v[88:91], v[88:91], v[4:7], 0
	s_add_i32 s22, s11, 1
	v_cmp_lt_i32_e32 vcc, s11, v93
	v_mov_b32_e32 v2, s11
	v_mov_b32_e32 v3, s22
	s_waitcnt vmcnt(14)
	v_mfma_f32_16x16x32_bf16 v[84:87], v[84:87], v[8:11], v[88:91]
	v_cndmask_b32_e32 v2, v2, v3, vcc
	v_add_u32_e32 v3, v94, v95
	v_cmp_le_i32_e32 vcc, v3, v155
	v_add_u32_e32 v88, 0x200, v3
	v_cmp_gt_i32_e64 s[0:1], v88, v155
	s_and_b64 vcc, vcc, s[0:1]
	s_nop 1
	v_mul_f32_e32 v84, 0x3e38aa3b, v84
	v_cndmask_b32_e32 v99, v203, v84, vcc
	v_add_u32_e32 v84, 0x201, v3
	v_cmp_lt_i32_e32 vcc, v3, v155
	v_cmp_gt_i32_e64 s[0:1], v84, v155
	s_and_b64 vcc, vcc, s[0:1]
	v_mul_f32_e32 v84, 0x3e38aa3b, v85
	v_cndmask_b32_e32 v100, v203, v84, vcc
	v_add_u32_e32 v84, 2, v3
	v_cmp_le_i32_e32 vcc, v84, v155
	v_add_u32_e32 v84, 0x202, v3
	v_cmp_gt_i32_e64 s[0:1], v84, v155
	s_and_b64 vcc, vcc, s[0:1]
	v_mul_f32_e32 v84, 0x3e38aa3b, v86
	s_waitcnt vmcnt(13)
	v_mfma_f32_16x16x32_bf16 v[80:83], v[80:83], v[4:7], 0
	v_cndmask_b32_e32 v101, v203, v84, vcc
	v_add_u32_e32 v84, v94, v96
	v_or_b32_e32 v85, 3, v84
	v_cmp_le_i32_e32 vcc, v85, v155
	v_add_u32_e32 v85, 0x200, v85
	v_cmp_gt_i32_e64 s[0:1], v85, v155
	s_waitcnt vmcnt(12)
	v_mfma_f32_16x16x32_bf16 v[76:79], v[76:79], v[8:11], v[80:83]
	s_and_b64 vcc, vcc, s[0:1]
	v_mul_f32_e32 v85, 0x3e38aa3b, v87
	v_cndmask_b32_e32 v102, v203, v85, vcc
	v_add_u32_e32 v80, 16, v3
	v_cmp_le_i32_e32 vcc, v80, v155
	v_add_u32_e32 v80, 0x210, v3
	v_cmp_gt_i32_e64 s[0:1], v80, v155
	s_and_b64 vcc, vcc, s[0:1]
	v_mul_f32_e32 v76, 0x3e38aa3b, v76
	v_cndmask_b32_e32 v103, v203, v76, vcc
	v_add_u32_e32 v76, 17, v3
	v_cmp_le_i32_e32 vcc, v76, v155
	v_add_u32_e32 v76, 0x211, v3
	v_cmp_gt_i32_e64 s[0:1], v76, v155
	s_and_b64 vcc, vcc, s[0:1]
	v_mul_f32_e32 v76, 0x3e38aa3b, v77
	v_cndmask_b32_e32 v104, v203, v76, vcc
	v_add_u32_e32 v76, 18, v3
	v_cmp_le_i32_e32 vcc, v76, v155
	v_add_u32_e32 v76, 0x212, v3
	v_cmp_gt_i32_e64 s[0:1], v76, v155
	s_waitcnt vmcnt(11)
	v_mfma_f32_16x16x32_bf16 v[72:75], v[72:75], v[4:7], 0
	s_and_b64 vcc, vcc, s[0:1]
	v_mul_f32_e32 v76, 0x3e38aa3b, v78
	v_cndmask_b32_e32 v105, v203, v76, vcc
	v_or_b32_e32 v76, 19, v84
	v_cmp_le_i32_e32 vcc, v76, v155
	v_add_u32_e32 v76, 0x200, v76
	v_cmp_gt_i32_e64 s[0:1], v76, v155
	s_waitcnt vmcnt(10)
	v_mfma_f32_16x16x32_bf16 v[68:71], v[68:71], v[8:11], v[72:75]
	s_and_b64 vcc, vcc, s[0:1]
	v_mul_f32_e32 v76, 0x3e38aa3b, v79
	v_cndmask_b32_e32 v106, v203, v76, vcc
	v_add_u32_e32 v72, 32, v3
	v_cmp_le_i32_e32 vcc, v72, v155
	v_add_u32_e32 v72, 0x220, v3
	v_cmp_gt_i32_e64 s[0:1], v72, v155
	s_and_b64 vcc, vcc, s[0:1]
	v_mul_f32_e32 v68, 0x3e38aa3b, v68
	v_cndmask_b32_e32 v107, v203, v68, vcc
	v_add_u32_e32 v68, 33, v3
	v_cmp_le_i32_e32 vcc, v68, v155
	v_add_u32_e32 v68, 0x221, v3
	v_cmp_gt_i32_e64 s[0:1], v68, v155
	s_and_b64 vcc, vcc, s[0:1]
	v_mul_f32_e32 v68, 0x3e38aa3b, v69
	v_cndmask_b32_e32 v108, v203, v68, vcc
	v_add_u32_e32 v68, 34, v3
	v_cmp_le_i32_e32 vcc, v68, v155
	v_add_u32_e32 v68, 0x222, v3
	v_cmp_gt_i32_e64 s[0:1], v68, v155
	s_waitcnt vmcnt(9)
	v_mfma_f32_16x16x32_bf16 v[52:55], v[52:55], v[4:7], 0
	s_and_b64 vcc, vcc, s[0:1]
	v_mul_f32_e32 v68, 0x3e38aa3b, v70
	v_cndmask_b32_e32 v109, v203, v68, vcc
	v_or_b32_e32 v68, 35, v84
	v_cmp_le_i32_e32 vcc, v68, v155
	v_add_u32_e32 v68, 0x200, v68
	v_cmp_gt_i32_e64 s[0:1], v68, v155
	s_waitcnt vmcnt(8)
	v_mfma_f32_16x16x32_bf16 v[44:47], v[44:47], v[8:11], v[52:55]
	s_and_b64 vcc, vcc, s[0:1]
	v_mul_f32_e32 v68, 0x3e38aa3b, v71
	v_cndmask_b32_e32 v110, v203, v68, vcc
	v_add_u32_e32 v52, 48, v3
	v_cmp_le_i32_e32 vcc, v52, v155
	v_add_u32_e32 v52, 0x230, v3
	v_cmp_gt_i32_e64 s[0:1], v52, v155
	s_and_b64 vcc, vcc, s[0:1]
	v_mul_f32_e32 v44, 0x3e38aa3b, v44
	v_cndmask_b32_e32 v111, v203, v44, vcc
	v_add_u32_e32 v44, 49, v3
	v_cmp_le_i32_e32 vcc, v44, v155
	v_add_u32_e32 v44, 0x231, v3
	v_cmp_gt_i32_e64 s[0:1], v44, v155
	s_and_b64 vcc, vcc, s[0:1]
	v_mul_f32_e32 v44, 0x3e38aa3b, v45
	v_cndmask_b32_e32 v112, v203, v44, vcc
	v_add_u32_e32 v44, 50, v3
	v_add_u32_e32 v3, 0x232, v3
	v_cmp_le_i32_e32 vcc, v44, v155
	v_cmp_gt_i32_e64 s[0:1], v3, v155
	s_and_b64 vcc, vcc, s[0:1]
	v_mul_f32_e32 v3, 0x3e38aa3b, v46
	v_cndmask_b32_e32 v113, v203, v3, vcc
	v_or_b32_e32 v3, 51, v84
	v_cmp_le_i32_e32 vcc, v3, v155
	v_add_u32_e32 v3, 0x200, v3
	v_cmp_gt_i32_e64 s[0:1], v3, v155
	s_and_b64 vcc, vcc, s[0:1]
	v_mul_f32_e32 v3, 0x3e38aa3b, v47
	v_mov_b32_e32 v92, v98
	v_lshl_add_u32 v2, v2, 6, v0
	v_cndmask_b32_e32 v114, v203, v3, vcc
	v_ashrrev_i32_e32 v3, 31, v2
	v_lshlrev_b64 v[44:45], 7, v[2:3]
	v_lshl_add_u64 v[44:45], v[142:143], 0, v[44:45]
	global_load_dwordx4 v[88:91], v[44:45], off
	global_load_dwordx4 v[84:87], v[44:45], off offset:1024
	global_load_dwordx4 v[80:83], v[44:45], off offset:2048
	global_load_dwordx4 v[76:79], v[44:45], off offset:3072
	v_add_co_u32_e32 v44, vcc, s33, v44
	s_nop 1
	v_addc_co_u32_e32 v45, vcc, 0, v45, vcc
	global_load_dwordx4 v[72:75], v[44:45], off
	global_load_dwordx4 v[68:71], v[44:45], off offset:1024
	global_load_dwordx4 v[52:55], v[44:45], off offset:2048
	s_nop 0
	global_load_dwordx4 v[44:47], v[44:45], off offset:3072
	v_max3_f32 v98, v99, s3, v100
	v_max3_f32 v98, v98, v101, v102
	v_max3_f32 v98, v98, v103, v104
	v_max3_f32 v98, v98, v105, v106
	v_max3_f32 v98, v98, v107, v108
	v_max3_f32 v98, v98, v109, v110
	v_max3_f32 v98, v98, v111, v112
	v_max3_f32 v98, v98, v113, v114
	v_mov_b32_e32 v115, v98
	s_nop 1
	v_permlane16_swap_b32_e32 v115, v98
	v_max_f32_e32 v98, v98, v115
	v_mov_b32_e32 v115, v98
	s_nop 1
	v_permlane32_swap_b32_e32 v115, v98
	v_max3_f32 v98, v92, v98, v115
	v_sub_f32_e32 v92, v92, v98
	v_exp_f32_e32 v92, v92
	s_nop 0
	v_cmp_neq_f32_e32 vcc, 1.0, v92
	s_cbranch_vccz .LBB0_102
	v_pk_mul_f32 v[26:27], v[26:27], v[92:93] op_sel_hi:[1,0]
	v_pk_mul_f32 v[24:25], v[24:25], v[92:93] op_sel_hi:[1,0]
	v_pk_mul_f32 v[22:23], v[22:23], v[92:93] op_sel_hi:[1,0]
	v_pk_mul_f32 v[20:21], v[20:21], v[92:93] op_sel_hi:[1,0]
	v_pk_mul_f32 v[18:19], v[18:19], v[92:93] op_sel_hi:[1,0]
	v_pk_mul_f32 v[16:17], v[16:17], v[92:93] op_sel_hi:[1,0]
	v_pk_mul_f32 v[14:15], v[14:15], v[92:93] op_sel_hi:[1,0]
	v_pk_mul_f32 v[12:13], v[12:13], v[92:93] op_sel_hi:[1,0]
	s_branch .LBB0_102

; #define EXP2F(x) __builtin_amdgcn_exp2f(x)
; #define SB0 __builtin_amdgcn_sched_barrier(0)
; __device__ __forceinline__ void softmax_update(f32x4 (&st)[4], float& m, float& lsum, f32x4 (&o)[4]) {
;   float mx = -1e30f;
; #pragma unroll
;   for (int kt = 0; kt < 4; ++kt)
; #pragma unroll
;     for (int r = 0; r < 4; ++r) mx = fmaxf(mx, st[kt][r]);
;   mx = fmaxf(mx, __shfl_xor(mx, 16));
;   mx = fmaxf(mx, __shfl_xor(mx, 32));
;   const float mnew = fmaxf(m, mx);
;   const float alpha = EXP2F(m - mnew);
;   float ps = 0.f;
; #pragma unroll
;   for (int kt = 0; kt < 4; ++kt)
; #pragma unroll
;     for (int r = 0; r < 4; ++r) {
;       const float pv = EXP2F(st[kt][r] - mnew);
;       st[kt][r] = pv;
;       ps += pv;
;     }
;   lsum = lsum * alpha + ps;
;   m = mnew;
;   if (__builtin_amdgcn_ballot_w64(alpha != 1.0f)) {
; #pragma unroll
;     for (int dt = 0; dt < 4; ++dt) o[dt] *= alpha;
;   }
; __device__ __forceinline__ void phase_nsa_attn(const Params& p, char* smem, volatile LAS unsigned* vb_) {
;     ...
;       for (int i = 0; i < ntot; ++i) {
;         const int j = jn;
;         if (i + 1 < ntot) advance();
;         const bool mine = (((j < 64) ? (my0 >> j) : (my1 >> (j - 64))) & 1ull) != 0ull;
;         const int lim2 = (mine ? ((j == cur) ? (s - j * 64) : 63) : -1) - q * 4;
;         f32x4 st[4];
;         qk64_lim(kA, qf, scale, lim2, st);
;         SB0;
;         k_load64(kA, Ks + (size_t)jn * 4096, lane);
;         SB0;
;         softmax_update(st, m, lsum, o);
;         pv64(vA, st, o);
;         SB0;
;         v_load64(vA, Vs + (size_t)jn * 4096, lane);
;         SB0;
;       }
.LBB0_178:
	s_cmp_lt_i32 s36, 64
	s_waitcnt vmcnt(15)
	v_mfma_f32_16x16x32_bf16 v[88:91], v[88:91], v[4:7], 0
	s_cselect_b64 vcc, -1, 0
	s_sub_i32 s0, s36, 64
	v_lshrrev_b64 v[2:3], s36, v[92:93]
	v_lshrrev_b64 v[98:99], s0, v[94:95]
	s_cmp_eq_u32 s36, s60
	v_cndmask_b32_e32 v0, v98, v2, vcc
	s_cselect_b64 vcc, -1, 0
	s_lshl_b32 s0, s36, 6
	v_subrev_u32_e32 v2, s0, v155
	v_and_b32_e32 v0, 1, v0
	s_waitcnt vmcnt(14)
	v_mfma_f32_16x16x32_bf16 v[84:87], v[84:87], v[8:11], v[88:91]
	v_cndmask_b32_e32 v2, 63, v2, vcc
	v_cmp_eq_u32_e32 vcc, 1, v0
	s_waitcnt vmcnt(13)
	v_mfma_f32_16x16x32_bf16 v[80:83], v[80:83], v[4:7], 0
	v_cndmask_b32_e32 v0, -1, v2, vcc
	v_sub_u32_e32 v0, v0, v150
	s_nop 1
	v_mul_f32_e32 v2, 0x3e38aa3b, v84
	v_cmp_lt_i32_e32 vcc, -1, v0
	s_waitcnt vmcnt(12)
	v_mfma_f32_16x16x32_bf16 v[76:79], v[76:79], v[8:11], v[80:83]
	v_cndmask_b32_e32 v101, v203, v2, vcc
	v_mul_f32_e32 v2, 0x3e38aa3b, v85
	s_waitcnt vmcnt(11)
	v_mfma_f32_16x16x32_bf16 v[60:63], v[60:63], v[4:7], 0
	v_cmp_lt_i32_e32 vcc, 0, v0
	s_nop 1
	v_cndmask_b32_e32 v99, v203, v2, vcc
	v_mul_f32_e32 v2, 0x3e38aa3b, v86
	v_cmp_lt_i32_e32 vcc, 1, v0
	s_waitcnt vmcnt(10)
	v_mfma_f32_16x16x32_bf16 v[52:55], v[52:55], v[8:11], v[60:63]
	v_cndmask_b32_e32 v98, v203, v2, vcc
	v_mul_f32_e32 v2, 0x3e38aa3b, v87
	v_cmp_lt_i32_e32 vcc, 2, v0
	s_waitcnt vmcnt(9)
	v_mfma_f32_16x16x32_bf16 v[44:47], v[44:47], v[4:7], 0
	v_cndmask_b32_e32 v3, v203, v2, vcc
	v_mul_f32_e32 v2, 0x3e38aa3b, v76
	v_cmp_lt_i32_e32 vcc, 15, v0
	s_waitcnt vmcnt(8)
	v_mfma_f32_16x16x32_bf16 v[28:31], v[28:31], v[8:11], v[44:47]
	v_cndmask_b32_e32 v105, v203, v2, vcc
	v_mul_f32_e32 v2, 0x3e38aa3b, v77
	v_cmp_lt_i32_e32 vcc, 16, v0
	s_nop 1
	v_cndmask_b32_e32 v103, v203, v2, vcc
	v_mul_f32_e32 v2, 0x3e38aa3b, v78
	v_cmp_lt_i32_e32 vcc, 17, v0
	s_nop 1
	v_cndmask_b32_e32 v102, v203, v2, vcc
	v_mul_f32_e32 v2, 0x3e38aa3b, v79
	v_cmp_lt_i32_e32 vcc, 18, v0
	s_nop 1
	v_cndmask_b32_e32 v100, v203, v2, vcc
	v_mul_f32_e32 v2, 0x3e38aa3b, v52
	v_cmp_lt_i32_e32 vcc, 31, v0
	s_nop 1
	v_cndmask_b32_e32 v108, v203, v2, vcc
	v_mul_f32_e32 v2, 0x3e38aa3b, v53
	v_cmp_lt_i32_e32 vcc, 32, v0
	s_nop 1
	v_cndmask_b32_e32 v107, v203, v2, vcc
	v_mul_f32_e32 v2, 0x3e38aa3b, v54
	v_cmp_lt_i32_e32 vcc, 33, v0
	s_nop 1
	v_cndmask_b32_e32 v106, v203, v2, vcc
	v_mul_f32_e32 v2, 0x3e38aa3b, v55
	v_cmp_lt_i32_e32 vcc, 34, v0
	s_nop 1
	v_cndmask_b32_e32 v104, v203, v2, vcc
	v_mul_f32_e32 v2, 0x3e38aa3b, v28
	v_cmp_lt_i32_e32 vcc, 47, v0
	s_nop 1
	v_cndmask_b32_e32 v109, v203, v2, vcc
	v_mul_f32_e32 v2, 0x3e38aa3b, v29
	v_cmp_lt_i32_e32 vcc, 48, v0
	s_nop 1
	v_cndmask_b32_e32 v110, v203, v2, vcc
	v_mul_f32_e32 v2, 0x3e38aa3b, v30
	v_cmp_lt_i32_e32 vcc, 49, v0
	s_nop 1
	v_cndmask_b32_e32 v111, v203, v2, vcc
	v_mul_f32_e32 v2, 0x3e38aa3b, v31
	v_cmp_lt_i32_e32 vcc, 50, v0
	s_nop 1
	v_cndmask_b32_e32 v112, v203, v2, vcc
	s_lshl_b64 s[0:1], s[58:59], 13
	v_lshl_add_u64 v[28:29], v[146:147], 0, s[0:1]
	global_load_dwordx4 v[88:91], v[28:29], off
	global_load_dwordx4 v[84:87], v[28:29], off offset:1024
	global_load_dwordx4 v[80:83], v[28:29], off offset:2048
	global_load_dwordx4 v[76:79], v[28:29], off offset:3072
	v_add_co_u32_e32 v28, vcc, s33, v28
	s_nop 1
	v_addc_co_u32_e32 v29, vcc, 0, v29, vcc
	global_load_dwordx4 v[60:63], v[28:29], off
	global_load_dwordx4 v[52:55], v[28:29], off offset:1024
	global_load_dwordx4 v[44:47], v[28:29], off offset:2048
	s_nop 0
	global_load_dwordx4 v[28:31], v[28:29], off offset:3072
	v_max3_f32 v0, v101, s3, v99
	v_max3_f32 v0, v0, v98, v3
	v_max3_f32 v0, v0, v105, v103
	v_max3_f32 v0, v0, v102, v100
	v_max3_f32 v0, v0, v108, v107
	v_max3_f32 v0, v0, v106, v104
	v_max3_f32 v0, v0, v109, v110
	v_max3_f32 v0, v0, v111, v112
	v_mov_b32_e32 v2, v0
	s_nop 1
	v_permlane16_swap_b32_e32 v2, v0
	v_max_f32_e32 v0, v0, v2
	v_mov_b32_e32 v2, v0
	s_nop 1
	v_permlane32_swap_b32_e32 v2, v0
	v_max3_f32 v2, v97, v0, v2
	v_sub_f32_e32 v0, v97, v2
	v_exp_f32_e32 v0, v0
	s_nop 0
	v_cmp_neq_f32_e32 vcc, 1.0, v0
	s_cbranch_vccz .LBB0_180
	v_pk_mul_f32 v[26:27], v[26:27], v[0:1] op_sel_hi:[1,0]
	v_pk_mul_f32 v[24:25], v[24:25], v[0:1] op_sel_hi:[1,0]
	v_pk_mul_f32 v[22:23], v[22:23], v[0:1] op_sel_hi:[1,0]
	v_pk_mul_f32 v[20:21], v[20:21], v[0:1] op_sel_hi:[1,0]
	v_pk_mul_f32 v[18:19], v[18:19], v[0:1] op_sel_hi:[1,0]
	v_pk_mul_f32 v[16:17], v[16:17], v[0:1] op_sel_hi:[1,0]
	v_pk_mul_f32 v[14:15], v[14:15], v[0:1] op_sel_hi:[1,0]
	v_pk_mul_f32 v[12:13], v[12:13], v[0:1] op_sel_hi:[1,0]
